# P3 loop: p1-chain K-fragment reads issued behind the first QK MFMA; head reads only the four p0 fragments
# baseline (speedup 1.0000x reference)
.Lk_top:
	ds_read_b128 v[80:83], v85 offset:16384
	ds_read_b128 v[202:205], v254 offset:16384
	ds_read_b128 v[194:197], v255 offset:16384
	ds_read_b128 v[186:189], v84 offset:16384
	s_cmp_ge_i32 s72, s98
	s_cbranch_scc1 .LBB0_325
	s_add_i32 m0, s1, s94
	s_add_i32 s4, s90, s1
	global_load_lds_dwordx4 v[220:221], off
	s_mov_b32 m0, s4
	s_add_i32 s4, s1, s66
	global_load_lds_dwordx4 v[218:219], off
	s_mov_b32 m0, s4
	global_load_lds_dwordx4 v[224:225], off
	global_load_lds_dwordx4 v[224:225], off offset:1024
.LBB0_325:
	s_waitcnt lgkmcnt(0)
	v_mfma_f32_32x32x16_bf16 v[96:111], v[80:83], v[144:147], v[64:79]
	ds_read_b128 v[198:201], v85 offset:20480
	ds_read_b128 v[190:193], v254 offset:20480
	ds_read_b128 v[246:249], v255 offset:20480
	ds_read_b128 v[250:253], v84 offset:20480
	v_mfma_f32_32x32x16_bf16 v[96:111], v[202:205], v[140:143], v[96:111]
	v_cvt_f32_i32_e32 v156, s100
	v_mfma_f32_32x32x16_bf16 v[96:111], v[194:197], v[136:139], v[96:111]
	v_fma_f32 v254, v208, v156, -v207
	v_mfma_f32_32x32x16_bf16 v[96:111], v[186:189], v[132:135], v[96:111]
	v_add_f32_e32 v255, v237, v254
	s_add_i32 s3, s79, 0xfffe8000
	s_and_b32 s3, s3, 0x18000
	v_add_u32_e32 v158, s3, v235
	v_add_u32_e32 v159, s3, v239
	v_add_u32_e32 v160, s3, v236
	v_add_u32_e32 v161, s3, v234
	ds_read_b64_tr_b16 v[182:183], v158 offset:32768
	ds_read_b64_tr_b16 v[184:185], v158 offset:34816
	ds_read_b64_tr_b16 v[178:179], v159 offset:32768
	ds_read_b64_tr_b16 v[180:181], v159 offset:34816
	ds_read_b64_tr_b16 v[148:149], v160 offset:32768
	ds_read_b64_tr_b16 v[150:151], v160 offset:34816
	ds_read_b64_tr_b16 v[152:153], v161 offset:32768
	ds_read_b64_tr_b16 v[154:155], v161 offset:34816
	s_waitcnt lgkmcnt(8)
	v_mfma_f32_32x32x16_bf16 v[80:95], v[198:201], v[144:147], v[64:79]
	v_add_f32_e32 v96, v254, v96
	v_exp_f32_e32 v96, v96
	v_add_f32_e32 v97, v254, v97
	v_exp_f32_e32 v97, v97
	v_add_f32_e32 v98, v254, v98
	v_exp_f32_e32 v98, v98
	v_add_f32_e32 v99, v254, v99
	v_exp_f32_e32 v99, v99
	v_mfma_f32_32x32x16_bf16 v[80:95], v[190:193], v[140:143], v[80:95]
	v_add_f32_e32 v100, v254, v100
	v_exp_f32_e32 v100, v100
	v_add_f32_e32 v101, v254, v101
	v_exp_f32_e32 v101, v101
	v_add_f32_e32 v102, v254, v102
	v_exp_f32_e32 v102, v102
	v_add_f32_e32 v103, v254, v103
	v_exp_f32_e32 v103, v103
	v_mfma_f32_32x32x16_bf16 v[80:95], v[246:249], v[136:139], v[80:95]
	v_add_f32_e32 v104, v254, v104
	v_exp_f32_e32 v104, v104
	v_add_f32_e32 v105, v254, v105
	v_exp_f32_e32 v105, v105
	v_add_f32_e32 v106, v254, v106
	v_exp_f32_e32 v106, v106
	v_add_f32_e32 v107, v254, v107
	v_exp_f32_e32 v107, v107
	v_mfma_f32_32x32x16_bf16 v[80:95], v[250:253], v[132:135], v[80:95]
	v_add_f32_e32 v108, v254, v108
	v_exp_f32_e32 v108, v108
	v_add_f32_e32 v109, v254, v109
	v_exp_f32_e32 v109, v109
	v_add_f32_e32 v110, v254, v110
	v_exp_f32_e32 v110, v110
	v_add_f32_e32 v111, v254, v111
	v_exp_f32_e32 v111, v111
	s_cmp_le_i32 s72, s101
	s_cbranch_scc0 .Lmask_blk
